# P5 epilogue issues one L2 prefetch line per lane for the next tile first K-tile (A band, B rows of pn+4)
# speedup vs baseline: 1.0721x; 1.0047x over previous
.LBB0_164:
	v_mov_b32 v198, v0
	s_lshl_b32 s33, s42, 7
	v_and_b32_e32 v202, 15, v198
	v_lshlrev_b32_e32 v197, 3, v202
	v_or_b32_e32 v194, s33, v197
	v_ashrrev_i32_e32 v195, 31, v194
	v_lshlrev_b64 v[42:43], 2, v[194:195]
	v_readlane_b32 s0, v254, 19
	v_lshl_add_u64 v[6:7], s[86:87], 0, v[42:43]
	v_readlane_b32 s1, v254, 20
	global_load_dwordx4 v[2:5], v[6:7], off offset:16
	global_load_dwordx4 v[18:21], v[6:7], off
	v_lshl_add_u64 v[6:7], s[0:1], 0, v[42:43]
	v_readlane_b32 s0, v254, 21
	v_readlane_b32 s1, v254, 22
	global_load_dwordx4 v[58:61], v[6:7], off offset:16
	global_load_dwordx4 v[62:65], v[6:7], off
	v_lshl_add_u64 v[10:11], s[0:1], 0, v[42:43]
	v_readlane_b32 s0, v254, 23
	v_readlane_b32 s1, v254, 24
	global_load_dwordx4 v[6:9], v[10:11], off offset:16
	global_load_dwordx4 v[22:25], v[10:11], off
	v_lshl_add_u64 v[10:11], s[0:1], 0, v[42:43]
	v_readlane_b32 s0, v254, 25
	v_readlane_b32 s1, v254, 26
	global_load_dwordx4 v[46:49], v[10:11], off offset:16
	global_load_dwordx4 v[34:37], v[10:11], off
	v_lshl_add_u64 v[14:15], s[0:1], 0, v[42:43]
	v_readlane_b32 s0, v254, 27
	v_readlane_b32 s1, v254, 28
	global_load_dwordx4 v[10:13], v[14:15], off offset:16
	global_load_dwordx4 v[26:29], v[14:15], off
	v_lshl_add_u64 v[14:15], s[0:1], 0, v[42:43]
	v_readlane_b32 s0, v254, 29
	v_readlane_b32 s1, v254, 30
	v_lshl_add_u64 v[30:31], s[88:89], 0, v[42:43]
	global_load_dwordx4 v[50:53], v[14:15], off offset:16
	global_load_dwordx4 v[38:41], v[14:15], off
	v_lshl_add_u64 v[42:43], s[0:1], 0, v[42:43]
	global_load_dwordx4 v[14:17], v[30:31], off offset:16
	s_nop 0
	global_load_dwordx4 v[30:33], v[30:31], off
	s_nop 0
	global_load_dwordx4 v[54:57], v[42:43], off offset:16
	s_nop 0
	global_load_dwordx4 v[42:45], v[42:43], off
	v_lshrrev_b32_e32 v199, 2, v198
	s_mov_b32 s0, 0xfffffc0
	v_and_or_b32 v199, v199, s0, v202
	s_movk_i32 s0, 0x210
	v_mul_lo_u32 v199, v199, s0
	v_cvt_pk_bf16_f32 v182, v182, v183
	v_cvt_pk_bf16_f32 v183, v184, v185
	v_lshrrev_b32_e32 v184, 1, v198
	v_add_u32_e32 v199, 0, v199
	v_and_b32_e32 v184, 24, v184
	v_and_b32_e32 v185, 0xc0, v198
	v_add3_u32 v184, v199, v185, v184
	v_cvt_pk_bf16_f32 v122, v122, v123
	v_cvt_pk_bf16_f32 v123, v124, v125
	v_cvt_pk_bf16_f32 v114, v114, v115
	v_cvt_pk_bf16_f32 v115, v116, v117
	v_add_u32_e32 v124, 0x6000, v184
	v_cvt_pk_bf16_f32 v116, v130, v131
	ds_write2_b64 v124, v[122:123], v[114:115] offset0:96 offset1:100
	v_cvt_pk_bf16_f32 v114, v138, v139
	v_cvt_pk_bf16_f32 v115, v140, v141
	v_cvt_pk_bf16_f32 v117, v132, v133
	ds_write2_b64 v124, v[114:115], v[116:117] offset0:128 offset1:132
	v_add_u32_e32 v116, 0x10800, v184
	v_cvt_pk_bf16_f32 v86, v86, v87
	v_cvt_pk_bf16_f32 v87, v88, v89
	v_add_u32_e32 v88, 0x14a20, v184
	v_cvt_pk_bf16_f32 v114, v142, v143
	v_cvt_pk_bf16_f32 v115, v144, v145
	ds_write_b64 v116, v[114:115]
	v_add_u32_e32 v116, 0x10820, v184
	ds_write_b64 v88, v[86:87]
	v_cvt_pk_bf16_f32 v86, v90, v91
	v_add_u32_e32 v88, 0x14b00, v184
	v_cvt_pk_bf16_f32 v114, v126, v127
	v_cvt_pk_bf16_f32 v115, v128, v129
	ds_write_b64 v116, v[114:115]
	v_add_u32_e32 v116, 0x10900, v184
	v_cvt_pk_bf16_f32 v102, v102, v103
	v_cvt_pk_bf16_f32 v103, v104, v105
	v_add_u32_e32 v104, 0x12920, v184
	v_cvt_pk_bf16_f32 v87, v92, v93
	ds_write_b64 v88, v[86:87]
	v_cvt_pk_bf16_f32 v78, v78, v79
	v_cvt_pk_bf16_f32 v79, v80, v81
	v_add_u32_e32 v80, 0x16b00, v184
	v_cvt_pk_bf16_f32 v70, v70, v71
	v_cvt_pk_bf16_f32 v71, v72, v73
	v_add_u32_e32 v72, 0x16b20, v184
	v_cvt_pk_bf16_f32 v66, v66, v67
	v_cvt_pk_bf16_f32 v67, v68, v69
	v_add_u32_e32 v68, 0x16c20, v184
	v_ashrrev_i32_e32 v86, 4, v198
	s_movk_i32 s16, 0x1080
	v_cvt_pk_bf16_f32 v178, v178, v179
	v_cvt_pk_bf16_f32 v179, v180, v181
	v_cvt_pk_bf16_f32 v166, v166, v167
	v_cvt_pk_bf16_f32 v167, v168, v169
	v_cvt_pk_bf16_f32 v162, v162, v163
	v_cvt_pk_bf16_f32 v163, v164, v165
	v_add_u32_e32 v168, 0x2000, v184
	v_cvt_pk_bf16_f32 v150, v150, v151
	v_cvt_pk_bf16_f32 v151, v152, v153
	v_cvt_pk_bf16_f32 v146, v146, v147
	v_cvt_pk_bf16_f32 v147, v148, v149
	v_add_u32_e32 v152, 0x4000, v184
	v_cvt_pk_bf16_f32 v114, v134, v135
	v_cvt_pk_bf16_f32 v115, v136, v137
	ds_write_b64 v116, v[114:115]
	v_add_u32_e32 v116, 0x10920, v184
	v_cvt_pk_bf16_f32 v110, v110, v111
	v_cvt_pk_bf16_f32 v111, v112, v113
	v_add_u32_e32 v112, 0x12900, v184
	ds_write_b64 v104, v[102:103]
	v_add_u32_e32 v104, 0x12a00, v184
	v_cvt_pk_bf16_f32 v98, v98, v99
	v_cvt_pk_bf16_f32 v99, v100, v101
	v_add_u32_e32 v100, 0x12a20, v184
	v_cvt_pk_bf16_f32 v94, v94, v95
	v_cvt_pk_bf16_f32 v95, v96, v97
	v_add_u32_e32 v96, 0x14a00, v184
	v_cvt_pk_bf16_f32 v82, v82, v83
	v_cvt_pk_bf16_f32 v83, v84, v85
	v_add_u32_e32 v84, 0x14b20, v184
	ds_write_b64 v80, v[78:79]
	ds_write_b64 v72, v[70:71]
	v_add_u32_e32 v72, 0x16c00, v184
	ds_write_b64 v68, v[66:67]
	v_cmp_lt_i32_e32 vcc, 0, v86
	v_cmp_gt_i32_e64 s[0:1], 1, v86
	v_lshlrev_b32_e32 v80, 4, v202
	v_mul_lo_u32 v66, v86, s16
	ds_write2_b64 v184, v[182:183], v[178:179] offset1:4
	v_cvt_pk_bf16_f32 v178, v190, v191
	v_cvt_pk_bf16_f32 v179, v192, v193
	v_cvt_pk_bf16_f32 v180, v186, v187
	v_cvt_pk_bf16_f32 v181, v188, v189
	ds_write2_b64 v184, v[178:179], v[180:181] offset0:32 offset1:36
	ds_write2_b64 v168, v[166:167], v[162:163] offset0:32 offset1:36
	v_cvt_pk_bf16_f32 v162, v174, v175
	v_cvt_pk_bf16_f32 v163, v176, v177
	v_cvt_pk_bf16_f32 v164, v170, v171
	v_cvt_pk_bf16_f32 v165, v172, v173
	ds_write2_b64 v168, v[162:163], v[164:165] offset0:64 offset1:68
	ds_write2_b64 v152, v[150:151], v[146:147] offset0:64 offset1:68
	v_cvt_pk_bf16_f32 v146, v158, v159
	v_cvt_pk_bf16_f32 v147, v160, v161
	v_cvt_pk_bf16_f32 v148, v154, v155
	v_cvt_pk_bf16_f32 v149, v156, v157
	ds_write2_b64 v152, v[146:147], v[148:149] offset0:96 offset1:100
	v_cvt_pk_bf16_f32 v114, v118, v119
	v_cvt_pk_bf16_f32 v115, v120, v121
	ds_write_b64 v116, v[114:115]
	ds_write_b64 v112, v[110:111]
	v_cvt_pk_bf16_f32 v102, v106, v107
	v_cvt_pk_bf16_f32 v103, v108, v109
	ds_write_b64 v104, v[102:103]
	ds_write_b64 v100, v[98:99]
	ds_write_b64 v96, v[94:95]
	ds_write_b64 v84, v[82:83]
	v_cvt_pk_bf16_f32 v70, v74, v75
	v_cvt_pk_bf16_f32 v71, v76, v77
	ds_write_b64 v72, v[70:71]
	s_waitcnt vmcnt(0) lgkmcnt(0)
	s_barrier
	s_add_i32 s52, s42, 4
	s_cmp_lt_i32 s52, 22
	s_cbranch_scc0 .Lp5_pf_skip
	v_readlane_b32 s54, v255, 33
	v_readlane_b32 s55, v255, 34
	v_readlane_b32 s56, v255, 35
	v_readlane_b32 s57, v255, 36
	s_lshl_b32 s53, s36, 19
	s_add_u32 s54, s54, s53
	s_addc_u32 s55, s55, 0
	s_lshl_b32 s53, s52, 19
	s_add_u32 s56, s56, s53
	s_addc_u32 s57, s57, 0
	v_readfirstlane_b32 s53, v0
	s_cmp_lt_u32 s53, 0x100
	s_cselect_b32 s54, s54, s56
	s_cselect_b32 s55, s55, s57
	v_and_b32_e32 v222, 0xff, v0
	v_lshlrev_b32_e32 v222, 11, v222
	global_load_dword v250, v222, s[54:55]
.Lp5_pf_skip:
	s_and_saveexec_b64 s[16:17], s[0:1]
	v_readlane_b32 s78, v255, 28
	s_xor_b64 s[0:1], exec, s[16:17]
	v_readlane_b32 s79, v255, 29
	s_movk_i32 s16, 0x1080
	v_lshlrev_b32_e32 v80, 4, v202
	v_mul_lo_u32 v66, v86, s16
	s_or_saveexec_b64 s[0:1], s[0:1]
	v_mov_b32_e32 v77, 0
	v_mov_b32_e32 v78, 0
	v_mov_b32_e32 v76, 0
	v_mov_b32_e32 v103, 0
	v_mov_b32_e32 v75, 0
	v_mov_b32_e32 v108, 0
	v_mov_b32_e32 v74, 0
	v_mov_b32_e32 v111, 0
	v_mov_b32_e32 v79, 0
	v_mov_b32_e32 v81, 0
	v_mov_b32_e32 v84, 0
	v_mov_b32_e32 v85, 0
	v_mov_b32_e32 v123, 0
	v_mov_b32_e32 v124, 0
	v_mov_b32_e32 v127, 0
	v_mov_b32_e32 v128, 0
	v_mov_b32_e32 v101, 0
	v_mov_b32_e32 v102, 0
	v_mov_b32_e32 v104, 0
	v_mov_b32_e32 v105, 0
	v_mov_b32_e32 v109, 0
	v_mov_b32_e32 v110, 0
	v_mov_b32_e32 v112, 0
	v_mov_b32_e32 v113, 0
	v_mov_b32_e32 v82, 0
	v_mov_b32_e32 v83, 0
	v_mov_b32_e32 v120, 0
	v_mov_b32_e32 v121, 0
	v_mov_b32_e32 v125, 0
	v_mov_b32_e32 v126, 0
	v_mov_b32_e32 v129, 0
	v_mov_b32_e32 v130, 0
	s_xor_b64 exec, exec, s[0:1]
	s_cbranch_execz .LBB0_168
	v_add3_u32 v67, 0, v66, v80
	v_add_u32_e32 v68, 0xfffffbe0, v67
	v_add_u32_e32 v72, 0xfffffce0, v67
	ds_read_b128 v[68:71], v68
	ds_read_b128 v[76:79], v72
	v_add_u32_e32 v72, 0xfffffdf0, v67
	v_add_u32_e32 v67, 0xfffffef0, v67
	ds_read_b128 v[88:91], v72
	ds_read_b128 v[92:95], v67
	s_waitcnt lgkmcnt(3)
	v_lshlrev_b32_e32 v111, 16, v68
	v_and_b32_e32 v74, 0xffff0000, v68
	s_waitcnt lgkmcnt(2)
	v_lshlrev_b32_e32 v113, 16, v76
	v_and_b32_e32 v112, 0xffff0000, v76
	s_waitcnt lgkmcnt(1)
	v_lshlrev_b32_e32 v128, 16, v88
	v_and_b32_e32 v127, 0xffff0000, v88
	s_waitcnt lgkmcnt(0)
	v_lshlrev_b32_e32 v130, 16, v92
	v_and_b32_e32 v129, 0xffff0000, v92
	v_lshlrev_b32_e32 v108, 16, v69
	v_and_b32_e32 v75, 0xffff0000, v69
	v_lshlrev_b32_e32 v110, 16, v77
	v_and_b32_e32 v109, 0xffff0000, v77
	v_lshlrev_b32_e32 v124, 16, v89
	v_and_b32_e32 v123, 0xffff0000, v89
	v_lshlrev_b32_e32 v126, 16, v93
	v_and_b32_e32 v125, 0xffff0000, v93
	v_lshlrev_b32_e32 v103, 16, v70
	v_and_b32_e32 v76, 0xffff0000, v70
	v_lshlrev_b32_e32 v105, 16, v78
	v_and_b32_e32 v104, 0xffff0000, v78
	v_lshlrev_b32_e32 v85, 16, v90
	v_and_b32_e32 v84, 0xffff0000, v90
	v_lshlrev_b32_e32 v121, 16, v94
	v_and_b32_e32 v120, 0xffff0000, v94
	v_lshlrev_b32_e32 v78, 16, v71
	v_and_b32_e32 v77, 0xffff0000, v71
	v_lshlrev_b32_e32 v102, 16, v79
	v_and_b32_e32 v101, 0xffff0000, v79
	v_lshlrev_b32_e32 v81, 16, v91
	v_and_b32_e32 v79, 0xffff0000, v91
	v_lshlrev_b32_e32 v83, 16, v95
	v_and_b32_e32 v82, 0xffff0000, v95
